# baseline (speedup 1.0000x reference)
; __device__ __forceinline__ void phase_prep(const Params& p, char* smraw) {
;     ...
;     auto conv_row = [&](int row, const f32x4 (&vin)[4]) {
;       const int tbl = row / (2 * NEXP), r2 = row - tbl * 2 * NEXP, ly = r2 / NEXP, e = r2 - ly * NEXP;
;       f32x4 v[4]; float m = 0.f;
; #pragma unroll
;       for (int j = 0; j < 4; ++j) {
;         v[j] = vin[j];
;         if (!tbl) { f32x4 g = *(const f32x4*)(p.norm_ffn + ly * D + (j * 64 + l) * 4); v[j] *= g; }
;         m = fmaxf(m, fmaxf(fmaxf(fabsf(v[j][0]), fabsf(v[j][1])), fmaxf(fabsf(v[j][2]), fabsf(v[j][3]))));
;       }
; #pragma unroll
;       for (int mm = 32; mm >= 1; mm >>= 1) m = fmaxf(m, __shfl_xor(m, mm));
;       const float qmax = tbl ? 6.f : 7.f;
;       const float inv = m > 0.f ? qmax / m : 0.f;
;     ...
;     auto row_src = [&](int row) -> const float* {
;       const int tbl = row / (2 * NEXP), r2 = row - tbl * 2 * NEXP;
;       return (tbl ? p.pv : p.pu) + (size_t)r2 * D;
;     };
;     for (int row = bid * 4 + w; row < 4 * NEXP; row += 2 * nb * 4) {
;       const int row2 = row + nb * 4;
;       const bool has2 = row2 < 4 * NEXP;
;       const float* s0 = row_src(row);
;       const float* s1 = row_src(has2 ? row2 : row);
;       f32x4 va[4], vb[4];
; #pragma unroll
;       for (int j = 0; j < 4; ++j) { va[j] = *(const f32x4*)(s0 + (j * 64 + l) * 4); vb[j] = *(const f32x4*)(s1 + (j * 64 + l) * 4); }
.LBB0_63:
	v_ashrrev_i32_e32 v1, 6, v34
	v_add_u32_e32 v1, s3, v1
	s_mov_b32 s3, 0x10000
	v_cmp_gt_i32_e32 vcc, s3, v1
	v_mbcnt_lo_u32_b32 v191, -1, 0
	s_and_saveexec_b64 s[0:1], vcc
	s_cbranch_execz .LBB0_135
	v_and_b32_e32 v4, 63, v34
	v_lshrrev_b32_e32 v5, 6, v34
	v_lshlrev_b32_e32 v1, 4, v4
	v_lshrrev_b32_e32 v2, 1, v4
	v_lshlrev_b32_e32 v2, 2, v2
	v_lshlrev_b32_e32 v3, 1, v4
	v_readfirstlane_b32 s9, v5
	v_and_b32_e32 v6, 1, v4
	s_nop 0
	v_cmp_eq_u32_e64 s[6:7], 0, v6
	s_lshl_b32 s4, s2, 2
	s_add_u32 s4, s4, s9
	s_lshl_b32 s5, s96, 2
	s_mov_b32 s8, -1
	v_readlane_b32 s18, v254, 26
	v_readlane_b32 s19, v254, 27
	v_readlane_b32 s20, v254, 28
	v_readlane_b32 s21, v254, 29
	v_readlane_b32 s22, v254, 48
	v_readlane_b32 s23, v254, 49
	v_readlane_b32 s24, v254, 0
	v_readlane_b32 s25, v254, 1
	v_readlane_b32 s26, v254, 2
	v_readlane_b32 s27, v254, 3
	s_nop 4
	s_mov_b32 s9, s4
	s_min_u32 s9, s9, 0xffff
	s_and_b32 s28, s9, 0x7fff
	s_lshl_b32 s28, s28, 12
	s_bitcmp1_b32 s9, 15
	s_cselect_b32 s12, s20, s18
	s_cselect_b32 s13, s21, s19
	s_add_u32 s12, s12, s28
	s_addc_u32 s13, s13, 0
	global_load_dwordx4 v[36:39], v1, s[12:13]
	global_load_dwordx4 v[40:43], v1, s[12:13] offset:1024
	global_load_dwordx4 v[44:47], v1, s[12:13] offset:2048
	global_load_dwordx4 v[48:51], v1, s[12:13] offset:3072
	global_load_dword v9, v1, s[12:13]
	global_load_dword v9, v1, s[12:13]
	global_load_dword v9, v1, s[12:13]
	global_load_dword v9, v1, s[12:13]
	global_load_dword v9, v1, s[12:13]
	s_mul_i32 s9, s5, 1
	s_add_u32 s9, s4, s9
	s_min_u32 s9, s9, 0xffff
	s_and_b32 s28, s9, 0x7fff
	s_lshl_b32 s28, s28, 12
	s_bitcmp1_b32 s9, 15
	s_cselect_b32 s12, s20, s18
	s_cselect_b32 s13, s21, s19
	s_add_u32 s12, s12, s28
	s_addc_u32 s13, s13, 0
	global_load_dwordx4 v[68:71], v1, s[12:13]
	global_load_dwordx4 v[72:75], v1, s[12:13] offset:1024
	global_load_dwordx4 v[76:79], v1, s[12:13] offset:2048
	global_load_dwordx4 v[80:83], v1, s[12:13] offset:3072
	global_load_dword v9, v1, s[12:13]
	global_load_dword v9, v1, s[12:13]
	global_load_dword v9, v1, s[12:13]
	global_load_dword v9, v1, s[12:13]
	global_load_dword v9, v1, s[12:13]
	s_mul_i32 s9, s5, 2
	s_add_u32 s9, s4, s9
	s_min_u32 s9, s9, 0xffff
	s_and_b32 s28, s9, 0x7fff
	s_lshl_b32 s28, s28, 12
	s_bitcmp1_b32 s9, 15
	s_cselect_b32 s12, s20, s18
	s_cselect_b32 s13, s21, s19
	s_add_u32 s12, s12, s28
	s_addc_u32 s13, s13, 0
	global_load_dwordx4 v[84:87], v1, s[12:13]
	global_load_dwordx4 v[88:91], v1, s[12:13] offset:1024
	global_load_dwordx4 v[92:95], v1, s[12:13] offset:2048
	global_load_dwordx4 v[96:99], v1, s[12:13] offset:3072
	global_load_dword v9, v1, s[12:13]
	global_load_dword v9, v1, s[12:13]
	global_load_dword v9, v1, s[12:13]
	global_load_dword v9, v1, s[12:13]
	global_load_dword v9, v1, s[12:13]
.Lmy_cv_body0:
	s_cmp_lt_u32 s4, 0x8000
	s_cbranch_scc0 .Lmy_cv_v0
	s_bfe_u32 s9, s4, 0x1000e
	s_cmp_eq_u32 s9, s8
	s_cbranch_scc1 .Lmy_cv_gok0
	s_mov_b32 s8, s9
	s_lshl_b32 s10, s9, 12
	s_add_u32 s10, s22, s10
	s_addc_u32 s11, s23, 0
	global_load_dwordx4 v[16:19], v1, s[10:11]
	global_load_dwordx4 v[20:23], v1, s[10:11] offset:1024
	global_load_dwordx4 v[24:27], v1, s[10:11] offset:2048
	global_load_dwordx4 v[28:31], v1, s[10:11] offset:3072
	s_waitcnt vmcnt(0)
.Lmy_cv_gok0:
	s_waitcnt vmcnt(23)
	v_pk_mul_f32 v[36:37], v[36:37], v[16:17]
	v_pk_mul_f32 v[38:39], v[38:39], v[18:19]
	v_pk_mul_f32 v[40:41], v[40:41], v[20:21]
	v_pk_mul_f32 v[42:43], v[42:43], v[22:23]
	v_pk_mul_f32 v[44:45], v[44:45], v[24:25]
	v_pk_mul_f32 v[46:47], v[46:47], v[26:27]
	v_pk_mul_f32 v[48:49], v[48:49], v[28:29]
	v_pk_mul_f32 v[50:51], v[50:51], v[30:31]
	v_max_f32_e64 v10, |v36|, |v37|
	v_max3_f32 v10, |v38|, |v39|, v10
	v_max3_f32 v10, |v40|, |v41|, v10
	v_max3_f32 v10, |v42|, |v43|, v10
	v_max3_f32 v10, |v44|, |v45|, v10
	v_max3_f32 v10, |v46|, |v47|, v10
	v_max3_f32 v10, |v48|, |v49|, v10
	v_max3_f32 v10, |v50|, |v51|, v10
	s_nop 1
	v_max_f32_dpp v10, v10, v10 quad_perm:[1,0,3,2] row_mask:0xf bank_mask:0xf bound_ctrl:1
	s_nop 1
	v_max_f32_dpp v10, v10, v10 quad_perm:[2,3,0,1] row_mask:0xf bank_mask:0xf bound_ctrl:1
	s_nop 1
	v_max_f32_dpp v10, v10, v10 row_half_mirror row_mask:0xf bank_mask:0xf bound_ctrl:1
	s_nop 1
	v_max_f32_dpp v10, v10, v10 row_mirror row_mask:0xf bank_mask:0xf bound_ctrl:1
	s_nop 0
	v_readlane_b32 s9, v10, 0
	v_readlane_b32 s10, v10, 16
	v_readlane_b32 s11, v10, 32
	v_readlane_b32 s28, v10, 48
	s_nop 1
	v_mov_b32_e32 v10, s9
	v_max_f32_e32 v10, s10, v10
	v_max_f32_e32 v10, s11, v10
	v_max_f32_e32 v10, s28, v10
	v_cmp_lt_f32_e64 s[10:11], 0, v10
	v_mov_b32_e32 v13, 0x40e00000
	v_div_scale_f32 v14, s[14:15], v10, v10, v13
	v_rcp_f32_e32 v15, v14
	v_div_scale_f32 v4, vcc, v13, v10, v13
	v_fma_f32 v5, -v14, v15, 1.0
	v_fmac_f32_e32 v15, v5, v15
	v_mul_f32_e32 v5, v4, v15
	v_fma_f32 v6, -v14, v5, v4
	v_fmac_f32_e32 v5, v6, v15
	v_fma_f32 v14, -v14, v5, v4
	v_div_fmas_f32 v14, v14, v15, v5
	v_div_fixup_f32 v7, v14, v10, v13
	v_cndmask_b32_e64 v11, 0, v7, s[10:11]
	v_mul_f32_e32 v100, v36, v11
	v_mul_f32_e32 v101, v37, v11
	v_mul_f32_e32 v102, v38, v11
	v_mul_f32_e32 v103, v39, v11
	v_mul_f32_e32 v104, v40, v11
	v_mul_f32_e32 v105, v41, v11
	v_mul_f32_e32 v106, v42, v11
	v_mul_f32_e32 v107, v43, v11
	v_mul_f32_e32 v108, v44, v11
	v_mul_f32_e32 v109, v45, v11
	v_mul_f32_e32 v110, v46, v11
	v_mul_f32_e32 v111, v47, v11
	v_mul_f32_e32 v112, v48, v11
	v_mul_f32_e32 v113, v49, v11
	v_mul_f32_e32 v114, v50, v11
	v_mul_f32_e32 v115, v51, v11
	s_mul_i32 s9, s5, 3
	s_add_u32 s9, s4, s9
	s_min_u32 s9, s9, 0xffff
	s_and_b32 s28, s9, 0x7fff
	s_lshl_b32 s28, s28, 12
	s_bitcmp1_b32 s9, 15
	s_cselect_b32 s12, s20, s18
	s_cselect_b32 s13, s21, s19
; __device__ __forceinline__ void phase_prep(const Params& p, char* smraw) {
;     ...
;       const float inv = m > 0.f ? qmax / m : 0.f;
; #pragma unroll
;       for (int j = 0; j < 4; ++j) {
;         if (tbl) {
;           unsigned d = 0u;
;           d = __builtin_amdgcn_cvt_scalef32_pk_fp4_f32(d, v[j][0] * inv, v[j][1] * inv, 1.0f, 0);
;           d = __builtin_amdgcn_cvt_scalef32_pk_fp4_f32(d, v[j][2] * inv, v[j][3] * inv, 1.0f, 1);
;           *(u16*)(p.Vq + ((size_t)(ly * 4 + j) * NEXP + e) * 128 + l * 2) = (u16)(d & 0xffffu);
;         } else {
;           const int q0 = __float2int_rn(v[j][0] * inv) + 8, q1 = __float2int_rn(v[j][1] * inv) + 8, q2 = __float2int_rn(v[j][2] * inv) + 8, q3 = __float2int_rn(v[j][3] * inv) + 8;
;           const int own = (q0 & 15) | ((q1 & 15) << 8) | ((q2 & 15) << 16) | ((q3 & 15) << 24);
;           const int nb2 = __shfl_xor(own, 1);
;           if ((l & 1) == 0) *(int*)(p.Uq + ((size_t)(ly * 4 + j) * NEXP + e) * 128 + (l >> 1) * 4) = own | (nb2 << 4);
;         }
;       }
;       if (l == 0) (tbl ? p.Vs : p.Us)[ly * NEXP + e] = m > 0.f ? m / qmax : 1.f;
	s_add_u32 s12, s12, s28
	s_addc_u32 s13, s13, 0
	global_load_dwordx4 v[36:39], v1, s[12:13]
	global_load_dwordx4 v[40:43], v1, s[12:13] offset:1024
	global_load_dwordx4 v[44:47], v1, s[12:13] offset:2048
	global_load_dwordx4 v[48:51], v1, s[12:13] offset:3072
	v_div_scale_f32 v14, s[14:15], v13, v13, v10
	v_rcp_f32_e32 v15, v14
	v_div_scale_f32 v4, vcc, v10, v13, v10
	v_fma_f32 v5, -v14, v15, 1.0
	v_fmac_f32_e32 v15, v5, v15
	v_mul_f32_e32 v5, v4, v15
	v_fma_f32 v6, -v14, v5, v4
	v_fmac_f32_e32 v5, v6, v15
	v_fma_f32 v14, -v14, v5, v4
	v_div_fmas_f32 v14, v14, v15, v5
	v_div_fixup_f32 v7, v14, v13, v10
	v_cndmask_b32_e64 v12, 1.0, v7, s[10:11]
	v_rndne_f32_e32 v100, v100
	v_rndne_f32_e32 v101, v101
	v_rndne_f32_e32 v102, v102
	v_rndne_f32_e32 v103, v103
	v_rndne_f32_e32 v104, v104
	v_rndne_f32_e32 v105, v105
	v_rndne_f32_e32 v106, v106
	v_rndne_f32_e32 v107, v107
	v_rndne_f32_e32 v108, v108
	v_rndne_f32_e32 v109, v109
	v_rndne_f32_e32 v110, v110
	v_rndne_f32_e32 v111, v111
	v_rndne_f32_e32 v112, v112
	v_rndne_f32_e32 v113, v113
	v_rndne_f32_e32 v114, v114
	v_rndne_f32_e32 v115, v115
	v_cvt_i32_f32_e32 v100, v100
	v_cvt_i32_f32_e32 v101, v101
	v_cvt_i32_f32_e32 v102, v102
	v_cvt_i32_f32_e32 v103, v103
	v_cvt_i32_f32_e32 v104, v104
	v_cvt_i32_f32_e32 v105, v105
	v_cvt_i32_f32_e32 v106, v106
	v_cvt_i32_f32_e32 v107, v107
	v_cvt_i32_f32_e32 v108, v108
	v_cvt_i32_f32_e32 v109, v109
	v_cvt_i32_f32_e32 v110, v110
	v_cvt_i32_f32_e32 v111, v111
	v_cvt_i32_f32_e32 v112, v112
	v_cvt_i32_f32_e32 v113, v113
	v_cvt_i32_f32_e32 v114, v114
	v_cvt_i32_f32_e32 v115, v115
	v_add_u32_e32 v100, 8, v100
	v_add_lshl_u32 v101, v101, 8, 8
	v_add_lshl_u32 v102, v102, 8, 16
	v_add_lshl_u32 v103, v103, 8, 24
	v_add_u32_e32 v104, 8, v104
	v_add_lshl_u32 v105, v105, 8, 8
	v_add_lshl_u32 v106, v106, 8, 16
	v_add_lshl_u32 v107, v107, 8, 24
	v_add_u32_e32 v108, 8, v108
	v_add_lshl_u32 v109, v109, 8, 8
	v_add_lshl_u32 v110, v110, 8, 16
	v_add_lshl_u32 v111, v111, 8, 24
	v_add_u32_e32 v112, 8, v112
	v_add_lshl_u32 v113, v113, 8, 8
	v_add_lshl_u32 v114, v114, 8, 16
	v_add_lshl_u32 v115, v115, 8, 24
	v_or3_b32 v100, v100, v101, v102
	v_or3_b32 v104, v104, v105, v106
	v_or3_b32 v108, v108, v109, v110
	v_or3_b32 v112, v112, v113, v114
	v_or_b32_e32 v100, v100, v103
	v_or_b32_e32 v104, v104, v107
	v_or_b32_e32 v108, v108, v111
	v_or_b32_e32 v112, v112, v115
	s_and_b32 s9, s4, 0x3fff
	s_lshl_b32 s9, s9, 7
	s_bfe_u32 s10, s4, 0x1000e
	s_lshl_b32 s10, s10, 23
	s_add_u32 s9, s9, s10
	v_mov_b32_dpp v101, v100 quad_perm:[1,0,3,2] row_mask:0xf bank_mask:0xf bound_ctrl:1
	v_mov_b32_dpp v105, v104 quad_perm:[1,0,3,2] row_mask:0xf bank_mask:0xf bound_ctrl:1
	v_mov_b32_dpp v109, v108 quad_perm:[1,0,3,2] row_mask:0xf bank_mask:0xf bound_ctrl:1
	v_mov_b32_dpp v113, v112 quad_perm:[1,0,3,2] row_mask:0xf bank_mask:0xf bound_ctrl:1
	v_add_u32_e32 v102, s9, v2
	s_add_u32 s9, s9, 0x200000
	v_add_u32_e32 v106, s9, v2
	s_add_u32 s9, s9, 0x200000
	v_add_u32_e32 v110, s9, v2
	s_add_u32 s9, s9, 0x200000
	v_add_u32_e32 v114, s9, v2
	v_cndmask_b32_e64 v103, v101, v100, s[6:7]
	v_cndmask_b32_e64 v101, v100, v101, s[6:7]
	v_cndmask_b32_e64 v107, v105, v104, s[6:7]
	v_cndmask_b32_e64 v105, v104, v105, s[6:7]
	v_cndmask_b32_e64 v111, v109, v108, s[6:7]
	v_cndmask_b32_e64 v109, v108, v109, s[6:7]
	v_cndmask_b32_e64 v115, v113, v112, s[6:7]
	v_cndmask_b32_e64 v113, v112, v113, s[6:7]
	v_lshl_or_b32 v100, v101, 4, v103
	v_lshl_or_b32 v104, v105, 4, v107
	v_lshl_or_b32 v108, v109, 4, v111
	v_lshl_or_b32 v112, v113, 4, v115
	global_store_dword v102, v100, s[88:89]
	global_store_dword v106, v104, s[88:89]
	global_store_dword v110, v108, s[88:89]
	global_store_dword v114, v112, s[88:89]
	s_and_b32 s9, s4, 0x7fff
	s_lshl_b32 s9, s9, 2
	v_mov_b32_e32 v4, s9
	global_store_dword v4, v12, s[24:25]
	s_branch .Lmy_cv_next0
; __device__ __forceinline__ void phase_prep(const Params& p, char* smraw) {
;     ...
;       const float qmax = tbl ? 6.f : 7.f;
;       const float inv = m > 0.f ? qmax / m : 0.f;
; #pragma unroll
;       for (int j = 0; j < 4; ++j) {
;         if (tbl) {
;           unsigned d = 0u;
;           d = __builtin_amdgcn_cvt_scalef32_pk_fp4_f32(d, v[j][0] * inv, v[j][1] * inv, 1.0f, 0);
;           d = __builtin_amdgcn_cvt_scalef32_pk_fp4_f32(d, v[j][2] * inv, v[j][3] * inv, 1.0f, 1);
;           *(u16*)(p.Vq + ((size_t)(ly * 4 + j) * NEXP + e) * 128 + l * 2) = (u16)(d & 0xffffu);
;         } else {
;           const int q0 = __float2int_rn(v[j][0] * inv) + 8, q1 = __float2int_rn(v[j][1] * inv) + 8, q2 = __float2int_rn(v[j][2] * inv) + 8, q3 = __float2int_rn(v[j][3] * inv) + 8;
;           const int own = (q0 & 15) | ((q1 & 15) << 8) | ((q2 & 15) << 16) | ((q3 & 15) << 24);
;           const int nb2 = __shfl_xor(own, 1);
;           if ((l & 1) == 0) *(int*)(p.Uq + ((size_t)(ly * 4 + j) * NEXP + e) * 128 + (l >> 1) * 4) = own | (nb2 << 4);
;         }
;       }
;       if (l == 0) (tbl ? p.Vs : p.Us)[ly * NEXP + e] = m > 0.f ? m / qmax : 1.f;
;     };
;     auto row_src = [&](int row) -> const float* {
;       const int tbl = row / (2 * NEXP), r2 = row - tbl * 2 * NEXP;
;       return (tbl ? p.pv : p.pu) + (size_t)r2 * D;
;     };
;     for (int row = bid * 4 + w; row < 4 * NEXP; row += 2 * nb * 4) {
.Lmy_cv_v0:
	s_waitcnt vmcnt(23)
	v_max_f32_e64 v10, |v36|, |v37|
	v_max3_f32 v10, |v38|, |v39|, v10
	v_max3_f32 v10, |v40|, |v41|, v10
	v_max3_f32 v10, |v42|, |v43|, v10
	v_max3_f32 v10, |v44|, |v45|, v10
	v_max3_f32 v10, |v46|, |v47|, v10
	v_max3_f32 v10, |v48|, |v49|, v10
	v_max3_f32 v10, |v50|, |v51|, v10
	s_nop 1
	v_max_f32_dpp v10, v10, v10 quad_perm:[1,0,3,2] row_mask:0xf bank_mask:0xf bound_ctrl:1
	s_nop 1
	v_max_f32_dpp v10, v10, v10 quad_perm:[2,3,0,1] row_mask:0xf bank_mask:0xf bound_ctrl:1
	s_nop 1
	v_max_f32_dpp v10, v10, v10 row_half_mirror row_mask:0xf bank_mask:0xf bound_ctrl:1
	s_nop 1
	v_max_f32_dpp v10, v10, v10 row_mirror row_mask:0xf bank_mask:0xf bound_ctrl:1
	s_nop 0
	v_readlane_b32 s9, v10, 0
	v_readlane_b32 s10, v10, 16
	v_readlane_b32 s11, v10, 32
	v_readlane_b32 s28, v10, 48
	s_nop 1
	v_mov_b32_e32 v10, s9
	v_max_f32_e32 v10, s10, v10
	v_max_f32_e32 v10, s11, v10
	v_max_f32_e32 v10, s28, v10
	v_cmp_lt_f32_e64 s[10:11], 0, v10
	v_mov_b32_e32 v13, 0x40c00000
	v_div_scale_f32 v14, s[14:15], v10, v10, v13
	v_rcp_f32_e32 v15, v14
	v_div_scale_f32 v4, vcc, v13, v10, v13
	v_fma_f32 v5, -v14, v15, 1.0
	v_fmac_f32_e32 v15, v5, v15
	v_mul_f32_e32 v5, v4, v15
	v_fma_f32 v6, -v14, v5, v4
	v_fmac_f32_e32 v5, v6, v15
	v_fma_f32 v14, -v14, v5, v4
	v_div_fmas_f32 v14, v14, v15, v5
	v_div_fixup_f32 v7, v14, v10, v13
	v_cndmask_b32_e64 v11, 0, v7, s[10:11]
	v_mul_f32_e32 v100, v36, v11
	v_mul_f32_e32 v101, v37, v11
	v_mul_f32_e32 v102, v38, v11
	v_mul_f32_e32 v103, v39, v11
	v_mul_f32_e32 v104, v40, v11
	v_mul_f32_e32 v105, v41, v11
	v_mul_f32_e32 v106, v42, v11
	v_mul_f32_e32 v107, v43, v11
	v_mul_f32_e32 v108, v44, v11
	v_mul_f32_e32 v109, v45, v11
	v_mul_f32_e32 v110, v46, v11
	v_mul_f32_e32 v111, v47, v11
	v_mul_f32_e32 v112, v48, v11
	v_mul_f32_e32 v113, v49, v11
	v_mul_f32_e32 v114, v50, v11
	v_mul_f32_e32 v115, v51, v11
	s_mul_i32 s9, s5, 3
	s_add_u32 s9, s4, s9
	s_min_u32 s9, s9, 0xffff
	s_and_b32 s28, s9, 0x7fff
	s_lshl_b32 s28, s28, 12
	s_bitcmp1_b32 s9, 15
	s_cselect_b32 s12, s20, s18
	s_cselect_b32 s13, s21, s19
	s_add_u32 s12, s12, s28
	s_addc_u32 s13, s13, 0
	global_load_dwordx4 v[36:39], v1, s[12:13]
	global_load_dwordx4 v[40:43], v1, s[12:13] offset:1024
	global_load_dwordx4 v[44:47], v1, s[12:13] offset:2048
	global_load_dwordx4 v[48:51], v1, s[12:13] offset:3072
	v_div_scale_f32 v14, s[14:15], v13, v13, v10
	v_rcp_f32_e32 v15, v14
	v_div_scale_f32 v4, vcc, v10, v13, v10
	v_fma_f32 v5, -v14, v15, 1.0
	v_fmac_f32_e32 v15, v5, v15
	v_mul_f32_e32 v5, v4, v15
	v_fma_f32 v6, -v14, v5, v4
	v_fmac_f32_e32 v5, v6, v15
	v_fma_f32 v14, -v14, v5, v4
	v_div_fmas_f32 v14, v14, v15, v5
	v_div_fixup_f32 v7, v14, v13, v10
	v_cndmask_b32_e64 v12, 1.0, v7, s[10:11]
	v_mov_b32_e32 v5, 0
	v_mov_b32_e32 v6, 0
	v_mov_b32_e32 v7, 0
	v_mov_b32_e32 v8, 0
	v_cvt_scalef32_pk_fp4_f32 v5, v100, v101, 1.0
	v_cvt_scalef32_pk_fp4_f32 v6, v104, v105, 1.0
	v_cvt_scalef32_pk_fp4_f32 v7, v108, v109, 1.0
	v_cvt_scalef32_pk_fp4_f32 v8, v112, v113, 1.0
	v_cvt_scalef32_pk_fp4_f32 v5, v102, v103, 1.0 op_sel:[0,0,1,0]
	v_cvt_scalef32_pk_fp4_f32 v6, v106, v107, 1.0 op_sel:[0,0,1,0]
	v_cvt_scalef32_pk_fp4_f32 v7, v110, v111, 1.0 op_sel:[0,0,1,0]
	v_cvt_scalef32_pk_fp4_f32 v8, v114, v115, 1.0 op_sel:[0,0,1,0]
	s_and_b32 s9, s4, 0x3fff
	s_lshl_b32 s9, s9, 7
	s_bfe_u32 s10, s4, 0x1000e
	s_lshl_b32 s10, s10, 23
	s_add_u32 s9, s9, s10
	v_add_u32_e32 v100, s9, v3
	s_add_u32 s9, s9, 0x200000
	v_add_u32_e32 v101, s9, v3
	s_add_u32 s9, s9, 0x200000
	v_add_u32_e32 v102, s9, v3
	s_add_u32 s9, s9, 0x200000
	v_add_u32_e32 v103, s9, v3
	global_store_short v100, v5, s[90:91]
	global_store_short v101, v6, s[90:91]
	global_store_short v102, v7, s[90:91]
	global_store_short v103, v8, s[90:91]
	s_and_b32 s9, s4, 0x7fff
	s_lshl_b32 s9, s9, 2
	v_mov_b32_e32 v4, s9
	global_store_dword v4, v12, s[26:27]
.Lmy_cv_next0:
	s_add_u32 s4, s4, s5
	s_cmp_lt_u32 s4, s3
	s_cbranch_scc0 .Lmy_cv_done

; __device__ __forceinline__ void phase_prep(const Params& p, char* smraw) {
;     ...
;         v[j] = vin[j];
;         if (!tbl) { f32x4 g = *(const f32x4*)(p.norm_ffn + ly * D + (j * 64 + l) * 4); v[j] *= g; }
;         m = fmaxf(m, fmaxf(fmaxf(fabsf(v[j][0]), fabsf(v[j][1])), fmaxf(fabsf(v[j][2]), fabsf(v[j][3]))));
;       }
; #pragma unroll
;       for (int mm = 32; mm >= 1; mm >>= 1) m = fmaxf(m, __shfl_xor(m, mm));
;       const float qmax = tbl ? 6.f : 7.f;
;       const float inv = m > 0.f ? qmax / m : 0.f;
; #pragma unroll
;       for (int j = 0; j < 4; ++j) {
;         if (tbl) {
;           unsigned d = 0u;
;           d = __builtin_amdgcn_cvt_scalef32_pk_fp4_f32(d, v[j][0] * inv, v[j][1] * inv, 1.0f, 0);
;           d = __builtin_amdgcn_cvt_scalef32_pk_fp4_f32(d, v[j][2] * inv, v[j][3] * inv, 1.0f, 1);
;           *(u16*)(p.Vq + ((size_t)(ly * 4 + j) * NEXP + e) * 128 + l * 2) = (u16)(d & 0xffffu);
;         } else {
;           const int q0 = __float2int_rn(v[j][0] * inv) + 8, q1 = __float2int_rn(v[j][1] * inv) + 8, q2 = __float2int_rn(v[j][2] * inv) + 8, q3 = __float2int_rn(v[j][3] * inv) + 8;
;           const int own = (q0 & 15) | ((q1 & 15) << 8) | ((q2 & 15) << 16) | ((q3 & 15) << 24);
;           const int nb2 = __shfl_xor(own, 1);
;           if ((l & 1) == 0) *(int*)(p.Uq + ((size_t)(ly * 4 + j) * NEXP + e) * 128 + (l >> 1) * 4) = own | (nb2 << 4);
.Lmy_cv_gok1:
	s_waitcnt vmcnt(23)
	v_pk_mul_f32 v[68:69], v[68:69], v[16:17]
	v_pk_mul_f32 v[70:71], v[70:71], v[18:19]
	v_pk_mul_f32 v[72:73], v[72:73], v[20:21]
	v_pk_mul_f32 v[74:75], v[74:75], v[22:23]
	v_pk_mul_f32 v[76:77], v[76:77], v[24:25]
	v_pk_mul_f32 v[78:79], v[78:79], v[26:27]
	v_pk_mul_f32 v[80:81], v[80:81], v[28:29]
	v_pk_mul_f32 v[82:83], v[82:83], v[30:31]
	v_max_f32_e64 v10, |v68|, |v69|
	v_max3_f32 v10, |v70|, |v71|, v10
	v_max3_f32 v10, |v72|, |v73|, v10
	v_max3_f32 v10, |v74|, |v75|, v10
	v_max3_f32 v10, |v76|, |v77|, v10
	v_max3_f32 v10, |v78|, |v79|, v10
	v_max3_f32 v10, |v80|, |v81|, v10
	v_max3_f32 v10, |v82|, |v83|, v10
	s_nop 1
	v_max_f32_dpp v10, v10, v10 quad_perm:[1,0,3,2] row_mask:0xf bank_mask:0xf bound_ctrl:1
	s_nop 1
	v_max_f32_dpp v10, v10, v10 quad_perm:[2,3,0,1] row_mask:0xf bank_mask:0xf bound_ctrl:1
	s_nop 1
	v_max_f32_dpp v10, v10, v10 row_half_mirror row_mask:0xf bank_mask:0xf bound_ctrl:1
	s_nop 1
	v_max_f32_dpp v10, v10, v10 row_mirror row_mask:0xf bank_mask:0xf bound_ctrl:1
	s_nop 0
	v_readlane_b32 s9, v10, 0
	v_readlane_b32 s10, v10, 16
	v_readlane_b32 s11, v10, 32
	v_readlane_b32 s28, v10, 48
	s_nop 1
	v_mov_b32_e32 v10, s9
	v_max_f32_e32 v10, s10, v10
	v_max_f32_e32 v10, s11, v10
	v_max_f32_e32 v10, s28, v10
	v_cmp_lt_f32_e64 s[10:11], 0, v10
	v_mov_b32_e32 v13, 0x40e00000
	v_div_scale_f32 v14, s[14:15], v10, v10, v13
	v_rcp_f32_e32 v15, v14
	v_div_scale_f32 v4, vcc, v13, v10, v13
	v_fma_f32 v5, -v14, v15, 1.0
	v_fmac_f32_e32 v15, v5, v15
	v_mul_f32_e32 v5, v4, v15
	v_fma_f32 v6, -v14, v5, v4
	v_fmac_f32_e32 v5, v6, v15
	v_fma_f32 v14, -v14, v5, v4
	v_div_fmas_f32 v14, v14, v15, v5
	v_div_fixup_f32 v7, v14, v10, v13
	v_cndmask_b32_e64 v11, 0, v7, s[10:11]
	v_mul_f32_e32 v100, v68, v11
	v_mul_f32_e32 v101, v69, v11
	v_mul_f32_e32 v102, v70, v11
	v_mul_f32_e32 v103, v71, v11
	v_mul_f32_e32 v104, v72, v11
	v_mul_f32_e32 v105, v73, v11
	v_mul_f32_e32 v106, v74, v11
	v_mul_f32_e32 v107, v75, v11
	v_mul_f32_e32 v108, v76, v11
	v_mul_f32_e32 v109, v77, v11
	v_mul_f32_e32 v110, v78, v11
	v_mul_f32_e32 v111, v79, v11
	v_mul_f32_e32 v112, v80, v11
	v_mul_f32_e32 v113, v81, v11
	v_mul_f32_e32 v114, v82, v11
	v_mul_f32_e32 v115, v83, v11
	s_mul_i32 s9, s5, 3
	s_add_u32 s9, s4, s9
	s_min_u32 s9, s9, 0xffff
	s_and_b32 s28, s9, 0x7fff
	s_lshl_b32 s28, s28, 12
	s_bitcmp1_b32 s9, 15
	s_cselect_b32 s12, s20, s18
	s_cselect_b32 s13, s21, s19
	s_add_u32 s12, s12, s28
	s_addc_u32 s13, s13, 0
	global_load_dwordx4 v[68:71], v1, s[12:13]
	global_load_dwordx4 v[72:75], v1, s[12:13] offset:1024
	global_load_dwordx4 v[76:79], v1, s[12:13] offset:2048
	global_load_dwordx4 v[80:83], v1, s[12:13] offset:3072
	v_div_scale_f32 v14, s[14:15], v13, v13, v10
	v_rcp_f32_e32 v15, v14
	v_div_scale_f32 v4, vcc, v10, v13, v10
	v_fma_f32 v5, -v14, v15, 1.0
	v_fmac_f32_e32 v15, v5, v15
	v_mul_f32_e32 v5, v4, v15
	v_fma_f32 v6, -v14, v5, v4
	v_fmac_f32_e32 v5, v6, v15
	v_fma_f32 v14, -v14, v5, v4
	v_div_fmas_f32 v14, v14, v15, v5
	v_div_fixup_f32 v7, v14, v13, v10
	v_cndmask_b32_e64 v12, 1.0, v7, s[10:11]
	v_rndne_f32_e32 v100, v100
	v_rndne_f32_e32 v101, v101
	v_rndne_f32_e32 v102, v102
	v_rndne_f32_e32 v103, v103
	v_rndne_f32_e32 v104, v104
	v_rndne_f32_e32 v105, v105
	v_rndne_f32_e32 v106, v106
	v_rndne_f32_e32 v107, v107
	v_rndne_f32_e32 v108, v108
	v_rndne_f32_e32 v109, v109
	v_rndne_f32_e32 v110, v110
	v_rndne_f32_e32 v111, v111
	v_rndne_f32_e32 v112, v112
	v_rndne_f32_e32 v113, v113
	v_rndne_f32_e32 v114, v114
	v_rndne_f32_e32 v115, v115
	v_cvt_i32_f32_e32 v100, v100
	v_cvt_i32_f32_e32 v101, v101
	v_cvt_i32_f32_e32 v102, v102
	v_cvt_i32_f32_e32 v103, v103
	v_cvt_i32_f32_e32 v104, v104
	v_cvt_i32_f32_e32 v105, v105
	v_cvt_i32_f32_e32 v106, v106
	v_cvt_i32_f32_e32 v107, v107
	v_cvt_i32_f32_e32 v108, v108
	v_cvt_i32_f32_e32 v109, v109
	v_cvt_i32_f32_e32 v110, v110
	v_cvt_i32_f32_e32 v111, v111
	v_cvt_i32_f32_e32 v112, v112
	v_cvt_i32_f32_e32 v113, v113
	v_cvt_i32_f32_e32 v114, v114
	v_cvt_i32_f32_e32 v115, v115
	v_add_u32_e32 v100, 8, v100
	v_add_lshl_u32 v101, v101, 8, 8
	v_add_lshl_u32 v102, v102, 8, 16
	v_add_lshl_u32 v103, v103, 8, 24
	v_add_u32_e32 v104, 8, v104
	v_add_lshl_u32 v105, v105, 8, 8
	v_add_lshl_u32 v106, v106, 8, 16
	v_add_lshl_u32 v107, v107, 8, 24
	v_add_u32_e32 v108, 8, v108
	v_add_lshl_u32 v109, v109, 8, 8
	v_add_lshl_u32 v110, v110, 8, 16
	v_add_lshl_u32 v111, v111, 8, 24
	v_add_u32_e32 v112, 8, v112
	v_add_lshl_u32 v113, v113, 8, 8
	v_add_lshl_u32 v114, v114, 8, 16
	v_add_lshl_u32 v115, v115, 8, 24
	v_or3_b32 v100, v100, v101, v102
	v_or3_b32 v104, v104, v105, v106
	v_or3_b32 v108, v108, v109, v110
	v_or3_b32 v112, v112, v113, v114
	v_or_b32_e32 v100, v100, v103
	v_or_b32_e32 v104, v104, v107
	v_or_b32_e32 v108, v108, v111
	v_or_b32_e32 v112, v112, v115
	s_and_b32 s9, s4, 0x3fff
	s_lshl_b32 s9, s9, 7
	s_bfe_u32 s10, s4, 0x1000e
	s_lshl_b32 s10, s10, 23
	s_add_u32 s9, s9, s10
	v_mov_b32_dpp v101, v100 quad_perm:[1,0,3,2] row_mask:0xf bank_mask:0xf bound_ctrl:1
	v_mov_b32_dpp v105, v104 quad_perm:[1,0,3,2] row_mask:0xf bank_mask:0xf bound_ctrl:1
	v_mov_b32_dpp v109, v108 quad_perm:[1,0,3,2] row_mask:0xf bank_mask:0xf bound_ctrl:1
	v_mov_b32_dpp v113, v112 quad_perm:[1,0,3,2] row_mask:0xf bank_mask:0xf bound_ctrl:1
	v_add_u32_e32 v102, s9, v2
	s_add_u32 s9, s9, 0x200000
	v_add_u32_e32 v106, s9, v2
	s_add_u32 s9, s9, 0x200000
	v_add_u32_e32 v110, s9, v2
	s_add_u32 s9, s9, 0x200000
	v_add_u32_e32 v114, s9, v2
	v_cndmask_b32_e64 v103, v101, v100, s[6:7]
	v_cndmask_b32_e64 v101, v100, v101, s[6:7]
	v_cndmask_b32_e64 v107, v105, v104, s[6:7]
	v_cndmask_b32_e64 v105, v104, v105, s[6:7]
	v_cndmask_b32_e64 v111, v109, v108, s[6:7]
	v_cndmask_b32_e64 v109, v108, v109, s[6:7]
	v_cndmask_b32_e64 v115, v113, v112, s[6:7]
	v_cndmask_b32_e64 v113, v112, v113, s[6:7]
	v_lshl_or_b32 v100, v101, 4, v103
	v_lshl_or_b32 v104, v105, 4, v107
	v_lshl_or_b32 v108, v109, 4, v111
	v_lshl_or_b32 v112, v113, 4, v115
	global_store_dword v102, v100, s[88:89]
	global_store_dword v106, v104, s[88:89]
	global_store_dword v110, v108, s[88:89]
	global_store_dword v114, v112, s[88:89]
	s_and_b32 s9, s4, 0x7fff
	s_lshl_b32 s9, s9, 2
	v_mov_b32_e32 v4, s9
	global_store_dword v4, v12, s[24:25]
	s_branch .Lmy_cv_next1
; __device__ __forceinline__ void phase_prep(const Params& p, char* smraw) {
;     ...
;       const float qmax = tbl ? 6.f : 7.f;
;       const float inv = m > 0.f ? qmax / m : 0.f;
; #pragma unroll
;       for (int j = 0; j < 4; ++j) {
;         if (tbl) {
;           unsigned d = 0u;
;           d = __builtin_amdgcn_cvt_scalef32_pk_fp4_f32(d, v[j][0] * inv, v[j][1] * inv, 1.0f, 0);
;           d = __builtin_amdgcn_cvt_scalef32_pk_fp4_f32(d, v[j][2] * inv, v[j][3] * inv, 1.0f, 1);
;           *(u16*)(p.Vq + ((size_t)(ly * 4 + j) * NEXP + e) * 128 + l * 2) = (u16)(d & 0xffffu);
;         } else {
;           const int q0 = __float2int_rn(v[j][0] * inv) + 8, q1 = __float2int_rn(v[j][1] * inv) + 8, q2 = __float2int_rn(v[j][2] * inv) + 8, q3 = __float2int_rn(v[j][3] * inv) + 8;
;           const int own = (q0 & 15) | ((q1 & 15) << 8) | ((q2 & 15) << 16) | ((q3 & 15) << 24);
;           const int nb2 = __shfl_xor(own, 1);
;           if ((l & 1) == 0) *(int*)(p.Uq + ((size_t)(ly * 4 + j) * NEXP + e) * 128 + (l >> 1) * 4) = own | (nb2 << 4);
;         }
;       }
;       if (l == 0) (tbl ? p.Vs : p.Us)[ly * NEXP + e] = m > 0.f ? m / qmax : 1.f;
.Lmy_cv_v1:
	s_waitcnt vmcnt(23)
	v_max_f32_e64 v10, |v68|, |v69|
	v_max3_f32 v10, |v70|, |v71|, v10
	v_max3_f32 v10, |v72|, |v73|, v10
	v_max3_f32 v10, |v74|, |v75|, v10
	v_max3_f32 v10, |v76|, |v77|, v10
	v_max3_f32 v10, |v78|, |v79|, v10
	v_max3_f32 v10, |v80|, |v81|, v10
	v_max3_f32 v10, |v82|, |v83|, v10
	s_nop 1
	v_max_f32_dpp v10, v10, v10 quad_perm:[1,0,3,2] row_mask:0xf bank_mask:0xf bound_ctrl:1
	s_nop 1
	v_max_f32_dpp v10, v10, v10 quad_perm:[2,3,0,1] row_mask:0xf bank_mask:0xf bound_ctrl:1
	s_nop 1
	v_max_f32_dpp v10, v10, v10 row_half_mirror row_mask:0xf bank_mask:0xf bound_ctrl:1
	s_nop 1
	v_max_f32_dpp v10, v10, v10 row_mirror row_mask:0xf bank_mask:0xf bound_ctrl:1
	s_nop 0
	v_readlane_b32 s9, v10, 0
	v_readlane_b32 s10, v10, 16
	v_readlane_b32 s11, v10, 32
	v_readlane_b32 s28, v10, 48
	s_nop 1
	v_mov_b32_e32 v10, s9
	v_max_f32_e32 v10, s10, v10
	v_max_f32_e32 v10, s11, v10
	v_max_f32_e32 v10, s28, v10
	v_cmp_lt_f32_e64 s[10:11], 0, v10
	v_mov_b32_e32 v13, 0x40c00000
	v_div_scale_f32 v14, s[14:15], v10, v10, v13
	v_rcp_f32_e32 v15, v14
	v_div_scale_f32 v4, vcc, v13, v10, v13
	v_fma_f32 v5, -v14, v15, 1.0
	v_fmac_f32_e32 v15, v5, v15
	v_mul_f32_e32 v5, v4, v15
	v_fma_f32 v6, -v14, v5, v4
	v_fmac_f32_e32 v5, v6, v15
	v_fma_f32 v14, -v14, v5, v4
	v_div_fmas_f32 v14, v14, v15, v5
	v_div_fixup_f32 v7, v14, v10, v13
	v_cndmask_b32_e64 v11, 0, v7, s[10:11]
	v_mul_f32_e32 v100, v68, v11
	v_mul_f32_e32 v101, v69, v11
	v_mul_f32_e32 v102, v70, v11
	v_mul_f32_e32 v103, v71, v11
	v_mul_f32_e32 v104, v72, v11
	v_mul_f32_e32 v105, v73, v11
	v_mul_f32_e32 v106, v74, v11
	v_mul_f32_e32 v107, v75, v11
	v_mul_f32_e32 v108, v76, v11
	v_mul_f32_e32 v109, v77, v11
	v_mul_f32_e32 v110, v78, v11
	v_mul_f32_e32 v111, v79, v11
	v_mul_f32_e32 v112, v80, v11
	v_mul_f32_e32 v113, v81, v11
	v_mul_f32_e32 v114, v82, v11
	v_mul_f32_e32 v115, v83, v11
	s_mul_i32 s9, s5, 3
	s_add_u32 s9, s4, s9
	s_min_u32 s9, s9, 0xffff
	s_and_b32 s28, s9, 0x7fff
	s_lshl_b32 s28, s28, 12
	s_bitcmp1_b32 s9, 15
	s_cselect_b32 s12, s20, s18
	s_cselect_b32 s13, s21, s19
	s_add_u32 s12, s12, s28
	s_addc_u32 s13, s13, 0
	global_load_dwordx4 v[68:71], v1, s[12:13]
	global_load_dwordx4 v[72:75], v1, s[12:13] offset:1024
	global_load_dwordx4 v[76:79], v1, s[12:13] offset:2048
	global_load_dwordx4 v[80:83], v1, s[12:13] offset:3072
	v_div_scale_f32 v14, s[14:15], v13, v13, v10
	v_rcp_f32_e32 v15, v14
	v_div_scale_f32 v4, vcc, v10, v13, v10
	v_fma_f32 v5, -v14, v15, 1.0
	v_fmac_f32_e32 v15, v5, v15
	v_mul_f32_e32 v5, v4, v15
	v_fma_f32 v6, -v14, v5, v4
	v_fmac_f32_e32 v5, v6, v15
	v_fma_f32 v14, -v14, v5, v4
	v_div_fmas_f32 v14, v14, v15, v5
	v_div_fixup_f32 v7, v14, v13, v10
	v_cndmask_b32_e64 v12, 1.0, v7, s[10:11]
	v_mov_b32_e32 v5, 0
	v_mov_b32_e32 v6, 0
	v_mov_b32_e32 v7, 0
	v_mov_b32_e32 v8, 0
	v_cvt_scalef32_pk_fp4_f32 v5, v100, v101, 1.0
	v_cvt_scalef32_pk_fp4_f32 v6, v104, v105, 1.0
	v_cvt_scalef32_pk_fp4_f32 v7, v108, v109, 1.0
	v_cvt_scalef32_pk_fp4_f32 v8, v112, v113, 1.0
	v_cvt_scalef32_pk_fp4_f32 v5, v102, v103, 1.0 op_sel:[0,0,1,0]
	v_cvt_scalef32_pk_fp4_f32 v6, v106, v107, 1.0 op_sel:[0,0,1,0]
	v_cvt_scalef32_pk_fp4_f32 v7, v110, v111, 1.0 op_sel:[0,0,1,0]
	v_cvt_scalef32_pk_fp4_f32 v8, v114, v115, 1.0 op_sel:[0,0,1,0]
	s_and_b32 s9, s4, 0x3fff
	s_lshl_b32 s9, s9, 7
	s_bfe_u32 s10, s4, 0x1000e
	s_lshl_b32 s10, s10, 23
	s_add_u32 s9, s9, s10
	v_add_u32_e32 v100, s9, v3
	s_add_u32 s9, s9, 0x200000
	v_add_u32_e32 v101, s9, v3
	s_add_u32 s9, s9, 0x200000
	v_add_u32_e32 v102, s9, v3
	s_add_u32 s9, s9, 0x200000
	v_add_u32_e32 v103, s9, v3
	global_store_short v100, v5, s[90:91]
	global_store_short v101, v6, s[90:91]
	global_store_short v102, v7, s[90:91]
	global_store_short v103, v8, s[90:91]
	s_and_b32 s9, s4, 0x7fff
	s_lshl_b32 s9, s9, 2
	v_mov_b32_e32 v4, s9
	global_store_dword v4, v12, s[26:27]

; __device__ __forceinline__ void phase_prep(const Params& p, char* smraw) {
;     ...
;         v[j] = vin[j];
;         if (!tbl) { f32x4 g = *(const f32x4*)(p.norm_ffn + ly * D + (j * 64 + l) * 4); v[j] *= g; }
;         m = fmaxf(m, fmaxf(fmaxf(fabsf(v[j][0]), fabsf(v[j][1])), fmaxf(fabsf(v[j][2]), fabsf(v[j][3]))));
;       }
; #pragma unroll
;       for (int mm = 32; mm >= 1; mm >>= 1) m = fmaxf(m, __shfl_xor(m, mm));
;       const float qmax = tbl ? 6.f : 7.f;
;       const float inv = m > 0.f ? qmax / m : 0.f;
; #pragma unroll
;       for (int j = 0; j < 4; ++j) {
;         if (tbl) {
;           unsigned d = 0u;
;           d = __builtin_amdgcn_cvt_scalef32_pk_fp4_f32(d, v[j][0] * inv, v[j][1] * inv, 1.0f, 0);
;           d = __builtin_amdgcn_cvt_scalef32_pk_fp4_f32(d, v[j][2] * inv, v[j][3] * inv, 1.0f, 1);
;           *(u16*)(p.Vq + ((size_t)(ly * 4 + j) * NEXP + e) * 128 + l * 2) = (u16)(d & 0xffffu);
;         } else {
;           const int q0 = __float2int_rn(v[j][0] * inv) + 8, q1 = __float2int_rn(v[j][1] * inv) + 8, q2 = __float2int_rn(v[j][2] * inv) + 8, q3 = __float2int_rn(v[j][3] * inv) + 8;
;           const int own = (q0 & 15) | ((q1 & 15) << 8) | ((q2 & 15) << 16) | ((q3 & 15) << 24);
;           const int nb2 = __shfl_xor(own, 1);
;           if ((l & 1) == 0) *(int*)(p.Uq + ((size_t)(ly * 4 + j) * NEXP + e) * 128 + (l >> 1) * 4) = own | (nb2 << 4);
.Lmy_cv_gok2:
	s_waitcnt vmcnt(23)
	v_pk_mul_f32 v[84:85], v[84:85], v[16:17]
	v_pk_mul_f32 v[86:87], v[86:87], v[18:19]
	v_pk_mul_f32 v[88:89], v[88:89], v[20:21]
	v_pk_mul_f32 v[90:91], v[90:91], v[22:23]
	v_pk_mul_f32 v[92:93], v[92:93], v[24:25]
	v_pk_mul_f32 v[94:95], v[94:95], v[26:27]
	v_pk_mul_f32 v[96:97], v[96:97], v[28:29]
	v_pk_mul_f32 v[98:99], v[98:99], v[30:31]
	v_max_f32_e64 v10, |v84|, |v85|
	v_max3_f32 v10, |v86|, |v87|, v10
	v_max3_f32 v10, |v88|, |v89|, v10
	v_max3_f32 v10, |v90|, |v91|, v10
	v_max3_f32 v10, |v92|, |v93|, v10
	v_max3_f32 v10, |v94|, |v95|, v10
	v_max3_f32 v10, |v96|, |v97|, v10
	v_max3_f32 v10, |v98|, |v99|, v10
	s_nop 1
	v_max_f32_dpp v10, v10, v10 quad_perm:[1,0,3,2] row_mask:0xf bank_mask:0xf bound_ctrl:1
	s_nop 1
	v_max_f32_dpp v10, v10, v10 quad_perm:[2,3,0,1] row_mask:0xf bank_mask:0xf bound_ctrl:1
	s_nop 1
	v_max_f32_dpp v10, v10, v10 row_half_mirror row_mask:0xf bank_mask:0xf bound_ctrl:1
	s_nop 1
	v_max_f32_dpp v10, v10, v10 row_mirror row_mask:0xf bank_mask:0xf bound_ctrl:1
	s_nop 0
	v_readlane_b32 s9, v10, 0
	v_readlane_b32 s10, v10, 16
	v_readlane_b32 s11, v10, 32
	v_readlane_b32 s28, v10, 48
	s_nop 1
	v_mov_b32_e32 v10, s9
	v_max_f32_e32 v10, s10, v10
	v_max_f32_e32 v10, s11, v10
	v_max_f32_e32 v10, s28, v10
	v_cmp_lt_f32_e64 s[10:11], 0, v10
	v_mov_b32_e32 v13, 0x40e00000
	v_div_scale_f32 v14, s[14:15], v10, v10, v13
	v_rcp_f32_e32 v15, v14
	v_div_scale_f32 v4, vcc, v13, v10, v13
	v_fma_f32 v5, -v14, v15, 1.0
	v_fmac_f32_e32 v15, v5, v15
	v_mul_f32_e32 v5, v4, v15
	v_fma_f32 v6, -v14, v5, v4
	v_fmac_f32_e32 v5, v6, v15
	v_fma_f32 v14, -v14, v5, v4
	v_div_fmas_f32 v14, v14, v15, v5
	v_div_fixup_f32 v7, v14, v10, v13
	v_cndmask_b32_e64 v11, 0, v7, s[10:11]
	v_mul_f32_e32 v100, v84, v11
	v_mul_f32_e32 v101, v85, v11
	v_mul_f32_e32 v102, v86, v11
	v_mul_f32_e32 v103, v87, v11
	v_mul_f32_e32 v104, v88, v11
	v_mul_f32_e32 v105, v89, v11
	v_mul_f32_e32 v106, v90, v11
	v_mul_f32_e32 v107, v91, v11
	v_mul_f32_e32 v108, v92, v11
	v_mul_f32_e32 v109, v93, v11
	v_mul_f32_e32 v110, v94, v11
	v_mul_f32_e32 v111, v95, v11
	v_mul_f32_e32 v112, v96, v11
	v_mul_f32_e32 v113, v97, v11
	v_mul_f32_e32 v114, v98, v11
	v_mul_f32_e32 v115, v99, v11
	s_mul_i32 s9, s5, 3
	s_add_u32 s9, s4, s9
	s_min_u32 s9, s9, 0xffff
	s_and_b32 s28, s9, 0x7fff
	s_lshl_b32 s28, s28, 12
	s_bitcmp1_b32 s9, 15
	s_cselect_b32 s12, s20, s18
	s_cselect_b32 s13, s21, s19
	s_add_u32 s12, s12, s28
	s_addc_u32 s13, s13, 0
	global_load_dwordx4 v[84:87], v1, s[12:13]
	global_load_dwordx4 v[88:91], v1, s[12:13] offset:1024
	global_load_dwordx4 v[92:95], v1, s[12:13] offset:2048
	global_load_dwordx4 v[96:99], v1, s[12:13] offset:3072
	v_div_scale_f32 v14, s[14:15], v13, v13, v10
	v_rcp_f32_e32 v15, v14
	v_div_scale_f32 v4, vcc, v10, v13, v10
	v_fma_f32 v5, -v14, v15, 1.0
	v_fmac_f32_e32 v15, v5, v15
	v_mul_f32_e32 v5, v4, v15
	v_fma_f32 v6, -v14, v5, v4
	v_fmac_f32_e32 v5, v6, v15
	v_fma_f32 v14, -v14, v5, v4
	v_div_fmas_f32 v14, v14, v15, v5
	v_div_fixup_f32 v7, v14, v13, v10
	v_cndmask_b32_e64 v12, 1.0, v7, s[10:11]
	v_rndne_f32_e32 v100, v100
	v_rndne_f32_e32 v101, v101
	v_rndne_f32_e32 v102, v102
	v_rndne_f32_e32 v103, v103
	v_rndne_f32_e32 v104, v104
	v_rndne_f32_e32 v105, v105
	v_rndne_f32_e32 v106, v106
	v_rndne_f32_e32 v107, v107
	v_rndne_f32_e32 v108, v108
	v_rndne_f32_e32 v109, v109
	v_rndne_f32_e32 v110, v110
	v_rndne_f32_e32 v111, v111
	v_rndne_f32_e32 v112, v112
	v_rndne_f32_e32 v113, v113
	v_rndne_f32_e32 v114, v114
	v_rndne_f32_e32 v115, v115
	v_cvt_i32_f32_e32 v100, v100
	v_cvt_i32_f32_e32 v101, v101
	v_cvt_i32_f32_e32 v102, v102
	v_cvt_i32_f32_e32 v103, v103
	v_cvt_i32_f32_e32 v104, v104
	v_cvt_i32_f32_e32 v105, v105
	v_cvt_i32_f32_e32 v106, v106
	v_cvt_i32_f32_e32 v107, v107
	v_cvt_i32_f32_e32 v108, v108
	v_cvt_i32_f32_e32 v109, v109
	v_cvt_i32_f32_e32 v110, v110
	v_cvt_i32_f32_e32 v111, v111
	v_cvt_i32_f32_e32 v112, v112
	v_cvt_i32_f32_e32 v113, v113
	v_cvt_i32_f32_e32 v114, v114
	v_cvt_i32_f32_e32 v115, v115
	v_add_u32_e32 v100, 8, v100
	v_add_lshl_u32 v101, v101, 8, 8
	v_add_lshl_u32 v102, v102, 8, 16
	v_add_lshl_u32 v103, v103, 8, 24
	v_add_u32_e32 v104, 8, v104
	v_add_lshl_u32 v105, v105, 8, 8
	v_add_lshl_u32 v106, v106, 8, 16
	v_add_lshl_u32 v107, v107, 8, 24
	v_add_u32_e32 v108, 8, v108
	v_add_lshl_u32 v109, v109, 8, 8
	v_add_lshl_u32 v110, v110, 8, 16
	v_add_lshl_u32 v111, v111, 8, 24
	v_add_u32_e32 v112, 8, v112
	v_add_lshl_u32 v113, v113, 8, 8
	v_add_lshl_u32 v114, v114, 8, 16
	v_add_lshl_u32 v115, v115, 8, 24
	v_or3_b32 v100, v100, v101, v102
	v_or3_b32 v104, v104, v105, v106
	v_or3_b32 v108, v108, v109, v110
	v_or3_b32 v112, v112, v113, v114
	v_or_b32_e32 v100, v100, v103
	v_or_b32_e32 v104, v104, v107
	v_or_b32_e32 v108, v108, v111
	v_or_b32_e32 v112, v112, v115
	s_and_b32 s9, s4, 0x3fff
	s_lshl_b32 s9, s9, 7
	s_bfe_u32 s10, s4, 0x1000e
	s_lshl_b32 s10, s10, 23
	s_add_u32 s9, s9, s10
	v_mov_b32_dpp v101, v100 quad_perm:[1,0,3,2] row_mask:0xf bank_mask:0xf bound_ctrl:1
	v_mov_b32_dpp v105, v104 quad_perm:[1,0,3,2] row_mask:0xf bank_mask:0xf bound_ctrl:1
	v_mov_b32_dpp v109, v108 quad_perm:[1,0,3,2] row_mask:0xf bank_mask:0xf bound_ctrl:1
	v_mov_b32_dpp v113, v112 quad_perm:[1,0,3,2] row_mask:0xf bank_mask:0xf bound_ctrl:1
	v_add_u32_e32 v102, s9, v2
	s_add_u32 s9, s9, 0x200000
	v_add_u32_e32 v106, s9, v2
	s_add_u32 s9, s9, 0x200000
	v_add_u32_e32 v110, s9, v2
	s_add_u32 s9, s9, 0x200000
	v_add_u32_e32 v114, s9, v2
	v_cndmask_b32_e64 v103, v101, v100, s[6:7]
	v_cndmask_b32_e64 v101, v100, v101, s[6:7]
	v_cndmask_b32_e64 v107, v105, v104, s[6:7]
	v_cndmask_b32_e64 v105, v104, v105, s[6:7]
	v_cndmask_b32_e64 v111, v109, v108, s[6:7]
	v_cndmask_b32_e64 v109, v108, v109, s[6:7]
	v_cndmask_b32_e64 v115, v113, v112, s[6:7]
	v_cndmask_b32_e64 v113, v112, v113, s[6:7]
	v_lshl_or_b32 v100, v101, 4, v103
	v_lshl_or_b32 v104, v105, 4, v107
	v_lshl_or_b32 v108, v109, 4, v111
	v_lshl_or_b32 v112, v113, 4, v115
	global_store_dword v102, v100, s[88:89]
	global_store_dword v106, v104, s[88:89]
	global_store_dword v110, v108, s[88:89]
	global_store_dword v114, v112, s[88:89]
	s_and_b32 s9, s4, 0x7fff
	s_lshl_b32 s9, s9, 2
	v_mov_b32_e32 v4, s9
	global_store_dword v4, v12, s[24:25]
	s_branch .Lmy_cv_next2
; __device__ __forceinline__ void phase_prep(const Params& p, char* smraw) {
;     ...
;       const float qmax = tbl ? 6.f : 7.f;
;       const float inv = m > 0.f ? qmax / m : 0.f;
; #pragma unroll
;       for (int j = 0; j < 4; ++j) {
;         if (tbl) {
;           unsigned d = 0u;
;           d = __builtin_amdgcn_cvt_scalef32_pk_fp4_f32(d, v[j][0] * inv, v[j][1] * inv, 1.0f, 0);
;           d = __builtin_amdgcn_cvt_scalef32_pk_fp4_f32(d, v[j][2] * inv, v[j][3] * inv, 1.0f, 1);
;           *(u16*)(p.Vq + ((size_t)(ly * 4 + j) * NEXP + e) * 128 + l * 2) = (u16)(d & 0xffffu);
;         } else {
;           const int q0 = __float2int_rn(v[j][0] * inv) + 8, q1 = __float2int_rn(v[j][1] * inv) + 8, q2 = __float2int_rn(v[j][2] * inv) + 8, q3 = __float2int_rn(v[j][3] * inv) + 8;
;           const int own = (q0 & 15) | ((q1 & 15) << 8) | ((q2 & 15) << 16) | ((q3 & 15) << 24);
;           const int nb2 = __shfl_xor(own, 1);
;           if ((l & 1) == 0) *(int*)(p.Uq + ((size_t)(ly * 4 + j) * NEXP + e) * 128 + (l >> 1) * 4) = own | (nb2 << 4);
;         }
;       }
;       if (l == 0) (tbl ? p.Vs : p.Us)[ly * NEXP + e] = m > 0.f ? m / qmax : 1.f;
;     };
;     auto row_src = [&](int row) -> const float* {
;       const int tbl = row / (2 * NEXP), r2 = row - tbl * 2 * NEXP;
;       return (tbl ? p.pv : p.pu) + (size_t)r2 * D;
;     };
;     for (int row = bid * 4 + w; row < 4 * NEXP; row += 2 * nb * 4) {
;     ...
;   for (size_t i = gtid; i < (size_t)2 * 2 * 128 * 128 / 4; i += gstride) {
;     f32x4 v = *(const f32x4*)(p.subkeys + i * 4);
;     u32x2 o; o[0] = cvtpk(v[0], v[1]); o[1] = cvtpk(v[2], v[3]);
;     *(u32x2*)(p.Sub + i * 4) = o;
.Lmy_cv_v2:
	s_waitcnt vmcnt(23)
	v_max_f32_e64 v10, |v84|, |v85|
	v_max3_f32 v10, |v86|, |v87|, v10
	v_max3_f32 v10, |v88|, |v89|, v10
	v_max3_f32 v10, |v90|, |v91|, v10
	v_max3_f32 v10, |v92|, |v93|, v10
	v_max3_f32 v10, |v94|, |v95|, v10
	v_max3_f32 v10, |v96|, |v97|, v10
	v_max3_f32 v10, |v98|, |v99|, v10
	s_nop 1
	v_max_f32_dpp v10, v10, v10 quad_perm:[1,0,3,2] row_mask:0xf bank_mask:0xf bound_ctrl:1
	s_nop 1
	v_max_f32_dpp v10, v10, v10 quad_perm:[2,3,0,1] row_mask:0xf bank_mask:0xf bound_ctrl:1
	s_nop 1
	v_max_f32_dpp v10, v10, v10 row_half_mirror row_mask:0xf bank_mask:0xf bound_ctrl:1
	s_nop 1
	v_max_f32_dpp v10, v10, v10 row_mirror row_mask:0xf bank_mask:0xf bound_ctrl:1
	s_nop 0
	v_readlane_b32 s9, v10, 0
	v_readlane_b32 s10, v10, 16
	v_readlane_b32 s11, v10, 32
	v_readlane_b32 s28, v10, 48
	s_nop 1
	v_mov_b32_e32 v10, s9
	v_max_f32_e32 v10, s10, v10
	v_max_f32_e32 v10, s11, v10
	v_max_f32_e32 v10, s28, v10
	v_cmp_lt_f32_e64 s[10:11], 0, v10
	v_mov_b32_e32 v13, 0x40c00000
	v_div_scale_f32 v14, s[14:15], v10, v10, v13
	v_rcp_f32_e32 v15, v14
	v_div_scale_f32 v4, vcc, v13, v10, v13
	v_fma_f32 v5, -v14, v15, 1.0
	v_fmac_f32_e32 v15, v5, v15
	v_mul_f32_e32 v5, v4, v15
	v_fma_f32 v6, -v14, v5, v4
	v_fmac_f32_e32 v5, v6, v15
	v_fma_f32 v14, -v14, v5, v4
	v_div_fmas_f32 v14, v14, v15, v5
	v_div_fixup_f32 v7, v14, v10, v13
	v_cndmask_b32_e64 v11, 0, v7, s[10:11]
	v_mul_f32_e32 v100, v84, v11
	v_mul_f32_e32 v101, v85, v11
	v_mul_f32_e32 v102, v86, v11
	v_mul_f32_e32 v103, v87, v11
	v_mul_f32_e32 v104, v88, v11
	v_mul_f32_e32 v105, v89, v11
	v_mul_f32_e32 v106, v90, v11
	v_mul_f32_e32 v107, v91, v11
	v_mul_f32_e32 v108, v92, v11
	v_mul_f32_e32 v109, v93, v11
	v_mul_f32_e32 v110, v94, v11
	v_mul_f32_e32 v111, v95, v11
	v_mul_f32_e32 v112, v96, v11
	v_mul_f32_e32 v113, v97, v11
	v_mul_f32_e32 v114, v98, v11
	v_mul_f32_e32 v115, v99, v11
	s_mul_i32 s9, s5, 3
	s_add_u32 s9, s4, s9
	s_min_u32 s9, s9, 0xffff
	s_and_b32 s28, s9, 0x7fff
	s_lshl_b32 s28, s28, 12
	s_bitcmp1_b32 s9, 15
	s_cselect_b32 s12, s20, s18
	s_cselect_b32 s13, s21, s19
	s_add_u32 s12, s12, s28
	s_addc_u32 s13, s13, 0
	global_load_dwordx4 v[84:87], v1, s[12:13]
	global_load_dwordx4 v[88:91], v1, s[12:13] offset:1024
	global_load_dwordx4 v[92:95], v1, s[12:13] offset:2048
	global_load_dwordx4 v[96:99], v1, s[12:13] offset:3072
	v_div_scale_f32 v14, s[14:15], v13, v13, v10
	v_rcp_f32_e32 v15, v14
	v_div_scale_f32 v4, vcc, v10, v13, v10
	v_fma_f32 v5, -v14, v15, 1.0
	v_fmac_f32_e32 v15, v5, v15
	v_mul_f32_e32 v5, v4, v15
	v_fma_f32 v6, -v14, v5, v4
	v_fmac_f32_e32 v5, v6, v15
	v_fma_f32 v14, -v14, v5, v4
	v_div_fmas_f32 v14, v14, v15, v5
	v_div_fixup_f32 v7, v14, v13, v10
	v_cndmask_b32_e64 v12, 1.0, v7, s[10:11]
	v_mov_b32_e32 v5, 0
	v_mov_b32_e32 v6, 0
	v_mov_b32_e32 v7, 0
	v_mov_b32_e32 v8, 0
	v_cvt_scalef32_pk_fp4_f32 v5, v100, v101, 1.0
	v_cvt_scalef32_pk_fp4_f32 v6, v104, v105, 1.0
	v_cvt_scalef32_pk_fp4_f32 v7, v108, v109, 1.0
	v_cvt_scalef32_pk_fp4_f32 v8, v112, v113, 1.0
	v_cvt_scalef32_pk_fp4_f32 v5, v102, v103, 1.0 op_sel:[0,0,1,0]
	v_cvt_scalef32_pk_fp4_f32 v6, v106, v107, 1.0 op_sel:[0,0,1,0]
	v_cvt_scalef32_pk_fp4_f32 v7, v110, v111, 1.0 op_sel:[0,0,1,0]
	v_cvt_scalef32_pk_fp4_f32 v8, v114, v115, 1.0 op_sel:[0,0,1,0]
	s_and_b32 s9, s4, 0x3fff
	s_lshl_b32 s9, s9, 7
	s_bfe_u32 s10, s4, 0x1000e
	s_lshl_b32 s10, s10, 23
	s_add_u32 s9, s9, s10
	v_add_u32_e32 v100, s9, v3
	s_add_u32 s9, s9, 0x200000
	v_add_u32_e32 v101, s9, v3
	s_add_u32 s9, s9, 0x200000
	v_add_u32_e32 v102, s9, v3
	s_add_u32 s9, s9, 0x200000
	v_add_u32_e32 v103, s9, v3
	global_store_short v100, v5, s[90:91]
	global_store_short v101, v6, s[90:91]
	global_store_short v102, v7, s[90:91]
	global_store_short v103, v8, s[90:91]
	s_and_b32 s9, s4, 0x7fff
	s_lshl_b32 s9, s9, 2
	v_mov_b32_e32 v4, s9
	global_store_dword v4, v12, s[26:27]
.Lmy_cv_next2:
	s_add_u32 s4, s4, s5
	s_cmp_lt_u32 s4, s3
	s_cbranch_scc0 .Lmy_cv_done
	s_branch .Lmy_cv_body0
.Lmy_cv_done:
.LBB0_135:
	s_or_b64 exec, exec, s[0:1]
	s_ashr_i32 s3, s2, 31
	s_lshl_b64 s[0:1], s[2:3], 8
	v_ashrrev_i32_e32 v35, 31, v34
	s_waitcnt vmcnt(0) lgkmcnt(0)
	v_lshl_add_u64 v[2:3], s[0:1], 0, v[34:35]
	s_ashr_i32 s97, s96, 31
	s_mov_b64 s[4:5], 0x4000
	s_lshl_b64 s[0:1], s[96:97], 8
	v_cmp_gt_u64_e32 vcc, s[4:5], v[2:3]
	s_and_saveexec_b64 s[4:5], vcc
	s_cbranch_execz .LBB0_138
	v_readlane_b32 s8, v254, 18
	v_readlane_b32 s10, v254, 20
	v_readlane_b32 s11, v254, 21
	v_readlane_b32 s14, v254, 24
	v_readlane_b32 s15, v254, 25
	s_lshl_b64 s[6:7], s[2:3], 12
	s_mov_b64 s[10:11], s[14:15]
	s_add_u32 s6, s10, s6
	v_readlane_b32 s9, v254, 19
	s_addc_u32 s7, s11, s7
	v_lshl_add_u64 v[4:5], v[34:35], 4, s[6:7]
	s_lshl_b64 s[6:7], s[96:97], 12
	s_lshl_b64 s[8:9], s[2:3], 11
	s_add_u32 s8, s86, s8
	v_readlane_b32 s12, v254, 22
	v_readlane_b32 s13, v254, 23
	s_addc_u32 s9, s87, s9
	v_lshl_add_u64 v[6:7], v[34:35], 3, s[8:9]
	s_lshl_b64 s[8:9], s[96:97], 11
	s_mov_b64 s[10:11], 0
	s_mov_b64 s[12:13], 0x3fff
	v_mov_b64_e32 v[8:9], v[2:3]
	v_readlane_b32 s16, v254, 26
	v_readlane_b32 s17, v254, 27
	v_readlane_b32 s18, v254, 28
	v_readlane_b32 s19, v254, 29
	v_readlane_b32 s20, v254, 30
	v_readlane_b32 s21, v254, 31
	v_readlane_b32 s22, v254, 32
	v_readlane_b32 s23, v254, 33
